# P7 up-proj GEMM: next tile first K-tile LDS-DMA loads issued before epilogue stores, counted vmcnt in warm prologue
# speedup vs baseline: 1.0054x; 1.0054x over previous
.LBB0_900:
	s_or_b64 exec, exec, s[40:41]
	s_cmpk_gt_u32 s2, 0x7ff
	s_cselect_b64 s[0:1], -1, 0
	s_xor_b64 s[6:7], s[60:61], -1
	s_or_b64 s[0:1], s[0:1], s[6:7]
	s_and_b64 vcc, exec, s[0:1]
	s_barrier
	s_cbranch_vccnz .LBB0_909
	s_lshl_b32 s34, s2, 8
	s_lshl_b32 s35, s83, 5
	s_lshl_b32 s36, s45, 5
	s_add_i32 s37, s83, s34
	s_mov_b32 s7, 0
	v_mov_b32_e32 v129, 0
	s_mov_b32 s38, 0x40000
	s_mov_b64 s[8:9], 0x80
	s_movk_i32 s39, 0x3c0
	s_mov_b64 s[10:11], 0x1ae0880
	s_mov_b64 s[12:13], 0x800100
	s_mov_b64 s[14:15], 0x1aa0900
	s_mov_b64 s[16:17], 0x840100
	s_mov_b64 s[18:19], 0x1ae0900
	s_mov_b64 s[20:21], 0x800180
	s_mov_b64 s[22:23], 0x1aa0980
	s_mov_b64 s[24:25], 0x840180
	s_mov_b64 s[26:27], 0x780
	v_mov_b32_e32 v142, 0x358637bd
	s_mov_b32 s40, 0x800000
	s_mov_b32 s41, 0x20000
	s_mov_b32 s42, 0x60000
	v_mov_b32_e32 v143, 1
	s_mov_b32 s43, s83
	s_mov_b32 s2, s83
	s_mov_b32 s54, 0
	s_mov_b32 s32, 0
	s_branch .LBB0_903
.LBB0_902:
	v_and_b32_e32 v144, 64, v241
	s_and_b32 s0, s2, 0x78
	v_xor_b32_e32 v132, 16, v241
	v_add_u32_e32 v144, 64, v144
	s_waitcnt vmcnt(0)
	s_mov_b32 s32, 0
	s_add_i32 s86, s2, s45
	s_cmpk_lt_u32 s86, 0x100
	s_cbranch_scc0 .Lp7_nopf
	v_readfirstlane_b32 s100, v238
	s_add_i32 s87, s86, s34
	s_lshr_b32 s87, s87, 4
	s_and_b32 s87, s87, 0x78
	s_and_b32 s88, s86, 7
	s_or_b32 s87, s87, s88
	s_lshl_b32 s88, s86, 16
	s_and_b32 s88, s88, 0x780000
	s_add_u32 s90, s64, s88
	s_addc_u32 s91, s65, 0
	s_lshl_b32 s89, s87, 19
	s_add_u32 s92, s46, s89
	s_addc_u32 s93, s47, 0
	s_bitset1_b32 s88, 18
	s_add_u32 s96, s64, s88
	s_addc_u32 s97, s65, 0
	s_bitset1_b32 s89, 18
	s_add_u32 s98, s46, s89
	s_addc_u32 s99, s47, 0
	s_lshl_b32 s100, s100, 4
	s_add_i32 s101, s44, s100
	s_mov_b32 m0, s101
	s_add_i32 s101, s101, 0x2000
	global_load_lds_dwordx4 v246, s[90:91]
	s_mov_b32 m0, s101
	s_add_i32 s101, s100, 0x2000
	global_load_lds_dwordx4 v247, s[90:91]
	s_mov_b32 m0, s100
	s_nop 0
	global_load_lds_dwordx4 v246, s[92:93]
	s_mov_b32 m0, s101
	s_add_i32 s101, s48, s100
	global_load_lds_dwordx4 v247, s[92:93]
	s_mov_b32 m0, s101
	s_add_i32 s101, s101, 0x2000
	global_load_lds_dwordx4 v246, s[96:97]
	s_mov_b32 m0, s101
	s_add_i32 s101, s100, 0x4000
	global_load_lds_dwordx4 v247, s[96:97]
	s_mov_b32 m0, s101
	s_add_i32 s101, s100, 0x6000
	global_load_lds_dwordx4 v246, s[98:99]
	s_mov_b32 m0, s101
	s_mov_b32 s32, 1
	global_load_lds_dwordx4 v247, s[98:99]
.Lp7_nopf:
	v_fmamk_f32 v141, v141, 0x3a800000, v142
	s_or_b32 s2, s30, s0
	v_cmp_lt_i32_e32 vcc, v132, v144
	v_mul_f32_e32 v144, 0x4b800000, v141
	v_cmp_gt_f32_e64 s[0:1], s40, v141
	v_mov_b32_e32 v128, v238
	v_cndmask_b32_e32 v132, v241, v132, vcc
	v_cndmask_b32_e64 v141, v141, v144, s[0:1]
	v_rsq_f32_e32 v141, v141
	v_and_b32_e32 v133, 16, v128
	v_cmp_eq_u32_e32 vcc, 0, v133
	v_and_or_b32 v130, v128, 15, s28
	v_mul_f32_e32 v133, 0x45800000, v141
	v_cndmask_b32_e64 v133, v141, v133, s[0:1]
	v_mul_f32_e32 v126, v133, v126
	v_mul_f32_e32 v127, v133, v127
	v_mul_f32_e32 v122, v133, v122
	v_mul_f32_e32 v123, v133, v123
	v_max_f32_e32 v126, 0, v126
	v_max_f32_e32 v127, 0, v127
	v_max_f32_e32 v122, 0, v122
	v_max_f32_e32 v123, 0, v123
	v_pk_mul_f32 v[126:127], v[126:127], v[126:127]
	v_mul_f32_e32 v120, v133, v120
	v_mul_f32_e32 v121, v133, v121
	v_pk_mul_f32 v[122:123], v[122:123], v[122:123]
	v_cvt_pk_bf16_f32 v126, v126, v127
	v_max_f32_e32 v120, 0, v120
	v_max_f32_e32 v121, 0, v121
	v_cvt_pk_bf16_f32 v122, v122, v123
	v_mov_b32_e32 v131, s29
	v_lshlrev_b32_e32 v132, 2, v132
	v_pk_mul_f32 v[120:121], v[120:121], v[120:121]
	v_cndmask_b32_e32 v123, v126, v122, vcc
	v_cvt_pk_bf16_f32 v127, v120, v121
	v_lshlrev_b64 v[120:121], 13, v[130:131]
	ds_bpermute_b32 v130, v132, v123
	v_mul_f32_e32 v124, v133, v124
	v_mul_f32_e32 v125, v133, v125
	v_max_f32_e32 v124, 0, v124
	v_max_f32_e32 v125, 0, v125
	v_pk_mul_f32 v[124:125], v[124:125], v[124:125]
	v_lshl_add_u64 v[120:121], s[50:51], 0, v[120:121]
	s_lshl_b32 s6, s2, 6
	v_cvt_pk_bf16_f32 v141, v124, v125
	v_lshl_add_u64 v[124:125], v[120:121], 0, s[6:7]
	v_fmamk_f32 v121, v140, 0x3a800000, v142
	s_waitcnt lgkmcnt(0)
	v_cndmask_b32_e32 v123, v122, v130, vcc
	v_mul_f32_e32 v122, 0x4b800000, v121
	v_cmp_gt_f32_e64 s[0:1], s40, v121
	v_cndmask_b32_e32 v120, v141, v127, vcc
	ds_bpermute_b32 v120, v132, v120
	v_cndmask_b32_e64 v121, v121, v122, s[0:1]
	v_rsq_f32_e32 v140, v121
	v_cndmask_b32_e32 v121, v130, v126, vcc
	v_lshrrev_b32_e32 v128, 2, v128
	v_and_b32_e32 v128, 12, v128
	v_mul_f32_e32 v126, 0x45800000, v140
	v_cndmask_b32_e64 v126, v140, v126, s[0:1]
	v_mul_f32_e32 v118, v126, v118
	v_mul_f32_e32 v119, v126, v119
	v_mul_f32_e32 v112, v126, v112
	v_mul_f32_e32 v113, v126, v113
	v_mul_f32_e32 v114, v126, v114
	v_mul_f32_e32 v115, v126, v115
	v_max_f32_e32 v118, 0, v118
	v_max_f32_e32 v119, 0, v119
	v_max_f32_e32 v112, 0, v112
	v_max_f32_e32 v113, 0, v113
	v_max_f32_e32 v114, 0, v114
	v_max_f32_e32 v115, 0, v115
	v_pk_mul_f32 v[118:119], v[118:119], v[118:119]
	v_pk_mul_f32 v[112:113], v[112:113], v[112:113]
	v_pk_mul_f32 v[114:115], v[114:115], v[114:115]
	v_cvt_pk_bf16_f32 v118, v118, v119
	v_cvt_pk_bf16_f32 v112, v112, v113
	v_cvt_pk_bf16_f32 v113, v114, v115
	v_cndmask_b32_e32 v115, v118, v113, vcc
	ds_bpermute_b32 v119, v132, v115
	v_mul_f32_e32 v116, v126, v116
	v_mul_f32_e32 v117, v126, v117
	v_max_f32_e32 v116, 0, v116
	v_max_f32_e32 v117, 0, v117
	v_pk_mul_f32 v[116:117], v[116:117], v[116:117]
	v_add_u32_e32 v144, 12, v128
	s_waitcnt lgkmcnt(1)
	v_cndmask_b32_e32 v122, v127, v120, vcc
	v_cvt_pk_bf16_f32 v127, v116, v117
	v_cndmask_b32_e32 v128, v144, v128, vcc
	v_cndmask_b32_e32 v114, v127, v112, vcc
	s_waitcnt lgkmcnt(0)
	v_cndmask_b32_e32 v115, v113, v119, vcc
	v_cndmask_b32_e32 v113, v119, v118, vcc
	v_fmamk_f32 v118, v139, 0x3a800000, v142
	ds_bpermute_b32 v130, v132, v114
	v_lshlrev_b32_e32 v128, 1, v128
	v_mul_f32_e32 v119, 0x4b800000, v118
	v_cmp_gt_f32_e64 s[0:1], s40, v118
	v_cndmask_b32_e32 v120, v120, v141, vcc
	v_lshl_add_u64 v[116:117], v[124:125], 0, v[128:129]
	v_cndmask_b32_e64 v118, v118, v119, s[0:1]
	global_store_dwordx4 v[116:117], v[120:123], off
	s_waitcnt lgkmcnt(0)
	v_cndmask_b32_e32 v114, v112, v130, vcc
	v_cndmask_b32_e32 v112, v130, v127, vcc
	v_rsq_f32_e32 v120, v118
	v_add_co_u32_e64 v118, s[2:3], s41, v116
	v_mul_f32_e32 v92, v133, v92
	s_nop 0
	v_addc_co_u32_e64 v119, s[2:3], 0, v117, s[2:3]
	global_store_dwordx4 v[118:119], v[112:115], off
	v_mul_f32_e32 v93, v133, v93
	v_mul_f32_e32 v88, v133, v88
	v_mul_f32_e32 v112, 0x45800000, v120
	v_cndmask_b32_e64 v112, v120, v112, s[0:1]
	v_mul_f32_e32 v108, v112, v108
	v_mul_f32_e32 v109, v112, v109
	v_mul_f32_e32 v110, v112, v110
	v_mul_f32_e32 v111, v112, v111
	v_mul_f32_e32 v106, v112, v106
	v_mul_f32_e32 v107, v112, v107
	v_max_f32_e32 v108, 0, v108
	v_max_f32_e32 v109, 0, v109
	v_max_f32_e32 v110, 0, v110
	v_max_f32_e32 v111, 0, v111
	v_max_f32_e32 v106, 0, v106
	v_max_f32_e32 v107, 0, v107
	v_pk_mul_f32 v[108:109], v[108:109], v[108:109]
	v_pk_mul_f32 v[110:111], v[110:111], v[110:111]
	v_pk_mul_f32 v[106:107], v[106:107], v[106:107]
	v_cvt_pk_bf16_f32 v108, v108, v109
	v_cvt_pk_bf16_f32 v109, v110, v111
	v_cvt_pk_bf16_f32 v106, v106, v107
	v_mul_f32_e32 v104, v112, v104
	v_mul_f32_e32 v105, v112, v105
	v_cndmask_b32_e32 v107, v109, v106, vcc
	v_max_f32_e32 v104, 0, v104
	v_max_f32_e32 v105, 0, v105
	ds_bpermute_b32 v110, v132, v107
	v_pk_mul_f32 v[104:105], v[104:105], v[104:105]
	v_mul_f32_e32 v89, v133, v89
	v_cvt_pk_bf16_f32 v104, v104, v105
	v_cndmask_b32_e32 v105, v108, v104, vcc
	ds_bpermute_b32 v111, v132, v105
	v_fmamk_f32 v105, v138, 0x3a800000, v142
	s_waitcnt lgkmcnt(1)
	v_cndmask_b32_e32 v107, v106, v110, vcc
	v_mul_f32_e32 v106, 0x4b800000, v105
	v_cmp_gt_f32_e64 s[0:1], s40, v105
	v_max_f32_e32 v92, 0, v92
	v_max_f32_e32 v93, 0, v93
	v_cndmask_b32_e64 v105, v105, v106, s[0:1]
	v_rsq_f32_e32 v113, v105
	s_waitcnt lgkmcnt(0)
	v_cndmask_b32_e32 v106, v104, v111, vcc
	v_cndmask_b32_e32 v104, v111, v108, vcc
	v_cndmask_b32_e32 v105, v110, v109, vcc
	v_mul_f32_e32 v108, 0x45800000, v113
	v_cndmask_b32_e64 v108, v113, v108, s[0:1]
	v_mul_f32_e32 v100, v108, v100
	v_mul_f32_e32 v101, v108, v101
	v_mul_f32_e32 v102, v108, v102
	v_mul_f32_e32 v103, v108, v103
	v_mul_f32_e32 v96, v108, v96
	v_mul_f32_e32 v97, v108, v97
	v_mul_f32_e32 v98, v108, v98
	v_mul_f32_e32 v99, v108, v99
	v_max_f32_e32 v100, 0, v100
	v_max_f32_e32 v101, 0, v101
	v_max_f32_e32 v102, 0, v102
	v_max_f32_e32 v103, 0, v103
	v_max_f32_e32 v96, 0, v96
	v_max_f32_e32 v97, 0, v97
	v_max_f32_e32 v98, 0, v98
	v_max_f32_e32 v99, 0, v99
	v_pk_mul_f32 v[100:101], v[100:101], v[100:101]
	v_pk_mul_f32 v[102:103], v[102:103], v[102:103]
	v_pk_mul_f32 v[96:97], v[96:97], v[96:97]
	v_pk_mul_f32 v[98:99], v[98:99], v[98:99]
	v_cvt_pk_bf16_f32 v100, v100, v101
	v_cvt_pk_bf16_f32 v101, v102, v103
	v_cvt_pk_bf16_f32 v102, v96, v97
	v_cvt_pk_bf16_f32 v98, v98, v99
	v_cndmask_b32_e32 v96, v100, v102, vcc
	v_cndmask_b32_e32 v97, v101, v98, vcc
	ds_bpermute_b32 v103, v132, v96
	ds_bpermute_b32 v109, v132, v97
	v_add_co_u32_e64 v96, s[0:1], s38, v116
	v_max_f32_e32 v88, 0, v88
	s_nop 0
	v_addc_co_u32_e64 v97, s[0:1], 0, v117, s[0:1]
	global_store_dwordx4 v[96:97], v[104:107], off
	s_waitcnt lgkmcnt(0)
	v_cndmask_b32_e32 v99, v98, v109, vcc
	v_cndmask_b32_e32 v98, v102, v103, vcc
	v_cndmask_b32_e32 v97, v109, v101, vcc
	v_cndmask_b32_e32 v96, v103, v100, vcc
	v_add_co_u32_e32 v100, vcc, s42, v116
	v_max_f32_e32 v89, 0, v89
	s_nop 0
	v_addc_co_u32_e32 v101, vcc, 0, v117, vcc
	global_store_dwordx4 v[100:101], v[96:99], off
	v_pk_mul_f32 v[92:93], v[92:93], v[92:93]
	v_pk_mul_f32 v[88:89], v[88:89], v[88:89]
	v_mov_b32_e32 v96, v238
	v_cvt_pk_bf16_f32 v99, v88, v89
	v_and_b32_e32 v97, 16, v96
	v_cmp_eq_u32_e32 vcc, 0, v97
	v_cvt_pk_bf16_f32 v97, v92, v93
	v_and_or_b32 v130, v96, 15, s28
	v_lshrrev_b32_e32 v96, 2, v96
	v_mul_f32_e32 v94, v133, v94
	v_mul_f32_e32 v95, v133, v95
	v_mul_f32_e32 v90, v133, v90
	v_mul_f32_e32 v91, v133, v91
	v_cndmask_b32_e32 v88, v97, v99, vcc
	v_and_b32_e32 v96, 12, v96
	v_max_f32_e32 v94, 0, v94
	v_max_f32_e32 v95, 0, v95
	v_max_f32_e32 v90, 0, v90
	v_max_f32_e32 v91, 0, v91
	ds_bpermute_b32 v101, v132, v88
	v_mul_f32_e32 v84, v126, v84
	v_mul_f32_e32 v85, v126, v85
	v_mul_f32_e32 v86, v126, v86
	v_mul_f32_e32 v87, v126, v87
	v_mul_f32_e32 v80, v126, v80
	v_mul_f32_e32 v81, v126, v81
	v_mul_f32_e32 v82, v126, v82
	v_mul_f32_e32 v83, v126, v83
	v_add_u32_e32 v98, 12, v96
	v_pk_mul_f32 v[94:95], v[94:95], v[94:95]
	v_pk_mul_f32 v[90:91], v[90:91], v[90:91]
	v_max_f32_e32 v84, 0, v84
	v_max_f32_e32 v85, 0, v85
	v_max_f32_e32 v86, 0, v86
	v_max_f32_e32 v87, 0, v87
	v_max_f32_e32 v80, 0, v80
	v_max_f32_e32 v81, 0, v81
	v_max_f32_e32 v82, 0, v82
	v_max_f32_e32 v83, 0, v83
	v_cndmask_b32_e32 v96, v98, v96, vcc
	v_cvt_pk_bf16_f32 v98, v94, v95
	v_cvt_pk_bf16_f32 v90, v90, v91
	v_pk_mul_f32 v[84:85], v[84:85], v[84:85]
	v_pk_mul_f32 v[86:87], v[86:87], v[86:87]
	v_pk_mul_f32 v[80:81], v[80:81], v[80:81]
	v_pk_mul_f32 v[82:83], v[82:83], v[82:83]
	v_cndmask_b32_e32 v89, v98, v90, vcc
	v_cvt_pk_bf16_f32 v84, v84, v85
	v_cvt_pk_bf16_f32 v85, v86, v87
	v_cvt_pk_bf16_f32 v86, v80, v81
	v_cvt_pk_bf16_f32 v82, v82, v83
	ds_bpermute_b32 v100, v132, v89
	v_lshlrev_b64 v[88:89], 13, v[130:131]
	v_cndmask_b32_e32 v80, v84, v86, vcc
	v_cndmask_b32_e32 v81, v85, v82, vcc
	v_mul_f32_e32 v76, v112, v76
	v_mul_f32_e32 v77, v112, v77
	v_mul_f32_e32 v78, v112, v78
	v_mul_f32_e32 v79, v112, v79
	v_mul_f32_e32 v72, v112, v72
	v_mul_f32_e32 v73, v112, v73
	v_lshl_add_u64 v[92:93], s[50:51], 0, v[88:89]
	s_waitcnt lgkmcnt(1)
	v_cndmask_b32_e32 v88, v101, v97, vcc
	ds_bpermute_b32 v87, v132, v81
	ds_bpermute_b32 v97, v132, v80
	v_max_f32_e32 v76, 0, v76
	v_max_f32_e32 v77, 0, v77
	v_max_f32_e32 v78, 0, v78
	v_max_f32_e32 v79, 0, v79
	v_max_f32_e32 v72, 0, v72
	v_max_f32_e32 v73, 0, v73
	v_pk_mul_f32 v[76:77], v[76:77], v[76:77]
	v_pk_mul_f32 v[78:79], v[78:79], v[78:79]
	v_pk_mul_f32 v[72:73], v[72:73], v[72:73]
	v_cvt_pk_bf16_f32 v76, v76, v77
	v_cvt_pk_bf16_f32 v77, v78, v79
	v_cvt_pk_bf16_f32 v78, v72, v73
	v_lshl_add_u64 v[94:95], v[92:93], 0, s[6:7]
	v_lshlrev_b32_e32 v128, 1, v96
	v_mul_f32_e32 v74, v112, v74
	v_mul_f32_e32 v75, v112, v75
	v_cndmask_b32_e32 v72, v76, v78, vcc
	s_waitcnt lgkmcnt(2)
	v_cndmask_b32_e32 v91, v90, v100, vcc
	v_cndmask_b32_e32 v90, v99, v101, vcc
	v_cndmask_b32_e32 v89, v100, v98, vcc
	v_lshl_add_u64 v[80:81], v[94:95], 0, v[128:129]
	v_max_f32_e32 v74, 0, v74
	v_max_f32_e32 v75, 0, v75
	ds_bpermute_b32 v79, v132, v72
	v_mul_f32_e32 v68, v108, v68
	v_mul_f32_e32 v69, v108, v69
	v_mul_f32_e32 v70, v108, v70
	v_mul_f32_e32 v71, v108, v71
	v_mul_f32_e32 v64, v108, v64
	v_mul_f32_e32 v65, v108, v65
	v_mul_f32_e32 v66, v108, v66
	v_mul_f32_e32 v67, v108, v67
	global_store_dwordx4 v[80:81], v[88:91], off offset:256
	s_waitcnt lgkmcnt(2)
	v_cndmask_b32_e32 v81, v87, v85, vcc
	s_waitcnt lgkmcnt(1)
	v_cndmask_b32_e32 v80, v97, v84, vcc
	s_or_b32 s30, s6, 0x100
	s_mov_b32 s31, s7
	v_lshl_add_u64 v[84:85], v[92:93], 0, v[128:129]
	v_pk_mul_f32 v[74:75], v[74:75], v[74:75]
	v_max_f32_e32 v68, 0, v68
	v_max_f32_e32 v69, 0, v69
	v_max_f32_e32 v70, 0, v70
	v_max_f32_e32 v71, 0, v71
	v_max_f32_e32 v64, 0, v64
	v_max_f32_e32 v65, 0, v65
	v_max_f32_e32 v66, 0, v66
	v_max_f32_e32 v67, 0, v67
	v_lshl_add_u64 v[84:85], v[84:85], 0, s[30:31]
	v_cvt_pk_bf16_f32 v74, v74, v75
	v_pk_mul_f32 v[68:69], v[68:69], v[68:69]
	v_pk_mul_f32 v[70:71], v[70:71], v[70:71]
	v_pk_mul_f32 v[64:65], v[64:65], v[64:65]
	v_pk_mul_f32 v[66:67], v[66:67], v[66:67]
	v_cndmask_b32_e32 v73, v77, v74, vcc
	v_add_co_u32_e64 v72, s[0:1], s41, v84
	v_cvt_pk_bf16_f32 v68, v68, v69
	v_cvt_pk_bf16_f32 v69, v70, v71
	v_cvt_pk_bf16_f32 v70, v64, v65
	v_cvt_pk_bf16_f32 v66, v66, v67
	v_cndmask_b32_e32 v83, v82, v87, vcc
	v_cndmask_b32_e32 v82, v86, v97, vcc
	ds_bpermute_b32 v86, v132, v73
	v_addc_co_u32_e64 v73, s[0:1], 0, v85, s[0:1]
	v_cndmask_b32_e32 v64, v68, v70, vcc
	v_cndmask_b32_e32 v65, v69, v66, vcc
	global_store_dwordx4 v[72:73], v[80:83], off
	s_waitcnt lgkmcnt(1)
	v_cndmask_b32_e32 v72, v79, v76, vcc
	ds_bpermute_b32 v71, v132, v64
	ds_bpermute_b32 v76, v132, v65
	v_add_co_u32_e64 v64, s[0:1], s38, v84
	s_waitcnt lgkmcnt(2)
	v_cndmask_b32_e32 v75, v74, v86, vcc
	v_cndmask_b32_e32 v74, v78, v79, vcc
	v_cndmask_b32_e32 v73, v86, v77, vcc
	v_addc_co_u32_e64 v65, s[0:1], 0, v85, s[0:1]
	global_store_dwordx4 v[64:65], v[72:75], off
	s_waitcnt lgkmcnt(0)
	v_cndmask_b32_e32 v67, v66, v76, vcc
	v_cndmask_b32_e32 v66, v70, v71, vcc
	v_cndmask_b32_e32 v65, v76, v69, vcc
	v_cndmask_b32_e32 v64, v71, v68, vcc
	v_add_co_u32_e32 v68, vcc, s42, v84
	s_addk_i32 s28, 0x80
	s_nop 0
	v_addc_co_u32_e32 v69, vcc, 0, v85, vcc
	global_store_dwordx4 v[68:69], v[64:67], off
	s_ashr_i32 s0, s28, 31
	v_fmamk_f32 v68, v137, 0x3a800000, v142
	v_mov_b32_e32 v65, s0
	v_mul_f32_e32 v69, 0x4b800000, v68
	v_cmp_gt_f32_e64 s[0:1], s40, v68
	v_mov_b32_e32 v66, v238
	s_add_i32 s54, s54, 1
	v_cndmask_b32_e64 v68, v68, v69, s[0:1]
	v_rsq_f32_e32 v68, v68
	v_and_b32_e32 v67, 16, v66
	v_cmp_eq_u32_e32 vcc, 0, v67
	v_and_or_b32 v64, v66, 15, s28
	v_mul_f32_e32 v67, 0x45800000, v68
	v_cndmask_b32_e64 v67, v68, v67, s[0:1]
	v_mul_f32_e32 v62, v67, v62
	v_mul_f32_e32 v63, v67, v63
	v_mul_f32_e32 v58, v67, v58
	v_mul_f32_e32 v59, v67, v59
	v_max_f32_e32 v62, 0, v62
	v_max_f32_e32 v63, 0, v63
	v_max_f32_e32 v58, 0, v58
	v_max_f32_e32 v59, 0, v59
	v_pk_mul_f32 v[62:63], v[62:63], v[62:63]
	v_mul_f32_e32 v56, v67, v56
	v_mul_f32_e32 v57, v67, v57
	v_pk_mul_f32 v[58:59], v[58:59], v[58:59]
	v_cvt_pk_bf16_f32 v62, v62, v63
	v_max_f32_e32 v56, 0, v56
	v_max_f32_e32 v57, 0, v57
	v_cvt_pk_bf16_f32 v58, v58, v59
	v_pk_mul_f32 v[56:57], v[56:57], v[56:57]
	v_cndmask_b32_e32 v59, v62, v58, vcc
	v_cvt_pk_bf16_f32 v63, v56, v57
	v_lshlrev_b64 v[56:57], 13, v[64:65]
	ds_bpermute_b32 v64, v132, v59
	v_mul_f32_e32 v60, v67, v60
	v_mul_f32_e32 v61, v67, v61
	v_max_f32_e32 v60, 0, v60
	v_max_f32_e32 v61, 0, v61
	v_pk_mul_f32 v[60:61], v[60:61], v[60:61]
	v_lshl_add_u64 v[56:57], s[50:51], 0, v[56:57]
	v_lshrrev_b32_e32 v66, 2, v66
	v_cvt_pk_bf16_f32 v68, v60, v61
	v_lshl_add_u64 v[60:61], v[56:57], 0, s[6:7]
	v_fmamk_f32 v57, v136, 0x3a800000, v142
	v_and_b32_e32 v66, 12, v66
	s_waitcnt lgkmcnt(0)
	v_cndmask_b32_e32 v59, v58, v64, vcc
	v_mul_f32_e32 v58, 0x4b800000, v57
	v_cmp_gt_f32_e64 s[0:1], s40, v57
	v_add_u32_e32 v69, 12, v66
	v_cndmask_b32_e32 v66, v69, v66, vcc
	v_cndmask_b32_e64 v57, v57, v58, s[0:1]
	v_rsq_f32_e32 v69, v57
	v_cndmask_b32_e32 v57, v64, v62, vcc
	v_cndmask_b32_e32 v56, v68, v63, vcc
	ds_bpermute_b32 v56, v132, v56
	v_mul_f32_e32 v62, 0x45800000, v69
	v_cndmask_b32_e64 v62, v69, v62, s[0:1]
	v_mul_f32_e32 v54, v62, v54
	v_mul_f32_e32 v55, v62, v55
	v_mul_f32_e32 v48, v62, v48
	v_mul_f32_e32 v49, v62, v49
	v_mul_f32_e32 v50, v62, v50
	v_mul_f32_e32 v51, v62, v51
	v_max_f32_e32 v54, 0, v54
	v_max_f32_e32 v55, 0, v55
	v_max_f32_e32 v48, 0, v48
	v_max_f32_e32 v49, 0, v49
	v_max_f32_e32 v50, 0, v50
	v_max_f32_e32 v51, 0, v51
	v_pk_mul_f32 v[54:55], v[54:55], v[54:55]
	v_pk_mul_f32 v[48:49], v[48:49], v[48:49]
	v_pk_mul_f32 v[50:51], v[50:51], v[50:51]
	v_cvt_pk_bf16_f32 v54, v54, v55
	v_cvt_pk_bf16_f32 v48, v48, v49
	v_cvt_pk_bf16_f32 v49, v50, v51
	v_cndmask_b32_e32 v51, v54, v49, vcc
	ds_bpermute_b32 v55, v132, v51
	v_mul_f32_e32 v52, v62, v52
	v_mul_f32_e32 v53, v62, v53
	v_max_f32_e32 v52, 0, v52
	v_max_f32_e32 v53, 0, v53
	v_pk_mul_f32 v[52:53], v[52:53], v[52:53]
	s_waitcnt lgkmcnt(1)
	v_cndmask_b32_e32 v58, v63, v56, vcc
	v_cvt_pk_bf16_f32 v63, v52, v53
	v_cndmask_b32_e32 v50, v63, v48, vcc
	s_waitcnt lgkmcnt(0)
	v_cndmask_b32_e32 v51, v49, v55, vcc
	v_cndmask_b32_e32 v49, v55, v54, vcc
	v_fmamk_f32 v54, v135, 0x3a800000, v142
	ds_bpermute_b32 v64, v132, v50
	v_lshlrev_b32_e32 v128, 1, v66
	v_mul_f32_e32 v55, 0x4b800000, v54
	v_cmp_gt_f32_e64 s[0:1], s40, v54
	v_cndmask_b32_e32 v56, v56, v68, vcc
	v_lshl_add_u64 v[52:53], v[60:61], 0, v[128:129]
	v_cndmask_b32_e64 v54, v54, v55, s[0:1]
	global_store_dwordx4 v[52:53], v[56:59], off
	s_waitcnt lgkmcnt(0)
	v_cndmask_b32_e32 v50, v48, v64, vcc
	v_cndmask_b32_e32 v48, v64, v63, vcc
	v_rsq_f32_e32 v56, v54
	v_add_co_u32_e64 v54, s[2:3], s41, v52
	v_mul_f32_e32 v28, v67, v28
	s_nop 0
	v_addc_co_u32_e64 v55, s[2:3], 0, v53, s[2:3]
	global_store_dwordx4 v[54:55], v[48:51], off
	v_mul_f32_e32 v29, v67, v29
	v_mul_f32_e32 v24, v67, v24
	v_mul_f32_e32 v48, 0x45800000, v56
	v_cndmask_b32_e64 v48, v56, v48, s[0:1]
	v_mul_f32_e32 v44, v48, v44
	v_mul_f32_e32 v45, v48, v45
	v_mul_f32_e32 v46, v48, v46
	v_mul_f32_e32 v47, v48, v47
	v_mul_f32_e32 v42, v48, v42
	v_mul_f32_e32 v43, v48, v43
	v_max_f32_e32 v44, 0, v44
	v_max_f32_e32 v45, 0, v45
	v_max_f32_e32 v46, 0, v46
	v_max_f32_e32 v47, 0, v47
	v_max_f32_e32 v42, 0, v42
	v_max_f32_e32 v43, 0, v43
	v_pk_mul_f32 v[44:45], v[44:45], v[44:45]
	v_pk_mul_f32 v[46:47], v[46:47], v[46:47]
	v_pk_mul_f32 v[42:43], v[42:43], v[42:43]
	v_cvt_pk_bf16_f32 v44, v44, v45
	v_cvt_pk_bf16_f32 v45, v46, v47
	v_cvt_pk_bf16_f32 v42, v42, v43
	v_mul_f32_e32 v40, v48, v40
	v_mul_f32_e32 v41, v48, v41
	v_cndmask_b32_e32 v43, v45, v42, vcc
	v_max_f32_e32 v40, 0, v40
	v_max_f32_e32 v41, 0, v41
	ds_bpermute_b32 v46, v132, v43
	v_pk_mul_f32 v[40:41], v[40:41], v[40:41]
	v_mul_f32_e32 v25, v67, v25
	v_cvt_pk_bf16_f32 v40, v40, v41
	v_cndmask_b32_e32 v41, v44, v40, vcc
	ds_bpermute_b32 v47, v132, v41
	v_fmamk_f32 v41, v134, 0x3a800000, v142
	s_waitcnt lgkmcnt(1)
	v_cndmask_b32_e32 v43, v42, v46, vcc
	v_mul_f32_e32 v42, 0x4b800000, v41
	v_cmp_gt_f32_e64 s[0:1], s40, v41
	v_max_f32_e32 v28, 0, v28
	v_max_f32_e32 v29, 0, v29
	v_cndmask_b32_e64 v41, v41, v42, s[0:1]
	v_rsq_f32_e32 v49, v41
	s_waitcnt lgkmcnt(0)
	v_cndmask_b32_e32 v42, v40, v47, vcc
	v_cndmask_b32_e32 v40, v47, v44, vcc
	v_cndmask_b32_e32 v41, v46, v45, vcc
	v_mul_f32_e32 v44, 0x45800000, v49
	v_cndmask_b32_e64 v44, v49, v44, s[0:1]
	v_mul_f32_e32 v36, v44, v36
	v_mul_f32_e32 v37, v44, v37
	v_mul_f32_e32 v38, v44, v38
	v_mul_f32_e32 v39, v44, v39
	v_mul_f32_e32 v32, v44, v32
	v_mul_f32_e32 v33, v44, v33
	v_mul_f32_e32 v34, v44, v34
	v_mul_f32_e32 v35, v44, v35
	v_max_f32_e32 v36, 0, v36
	v_max_f32_e32 v37, 0, v37
	v_max_f32_e32 v38, 0, v38
	v_max_f32_e32 v39, 0, v39
	v_max_f32_e32 v32, 0, v32
	v_max_f32_e32 v33, 0, v33
	v_max_f32_e32 v34, 0, v34
	v_max_f32_e32 v35, 0, v35
	v_pk_mul_f32 v[36:37], v[36:37], v[36:37]
	v_pk_mul_f32 v[38:39], v[38:39], v[38:39]
	v_pk_mul_f32 v[32:33], v[32:33], v[32:33]
	v_pk_mul_f32 v[34:35], v[34:35], v[34:35]
	v_cvt_pk_bf16_f32 v36, v36, v37
	v_cvt_pk_bf16_f32 v37, v38, v39
	v_cvt_pk_bf16_f32 v38, v32, v33
	v_cvt_pk_bf16_f32 v34, v34, v35
	v_cndmask_b32_e32 v32, v36, v38, vcc
	v_cndmask_b32_e32 v33, v37, v34, vcc
	ds_bpermute_b32 v39, v132, v32
	ds_bpermute_b32 v45, v132, v33
	v_add_co_u32_e64 v32, s[0:1], s38, v52
	v_max_f32_e32 v24, 0, v24
	s_nop 0
	v_addc_co_u32_e64 v33, s[0:1], 0, v53, s[0:1]
	global_store_dwordx4 v[32:33], v[40:43], off
	s_waitcnt lgkmcnt(0)
	v_cndmask_b32_e32 v35, v34, v45, vcc
	v_cndmask_b32_e32 v34, v38, v39, vcc
	v_cndmask_b32_e32 v33, v45, v37, vcc
	v_cndmask_b32_e32 v32, v39, v36, vcc
	v_add_co_u32_e32 v36, vcc, s42, v52
	v_max_f32_e32 v25, 0, v25
	s_nop 0
	v_addc_co_u32_e32 v37, vcc, 0, v53, vcc
	global_store_dwordx4 v[36:37], v[32:35], off
	v_pk_mul_f32 v[28:29], v[28:29], v[28:29]
	v_pk_mul_f32 v[24:25], v[24:25], v[24:25]
	v_mov_b32_e32 v32, v238
	v_cvt_pk_bf16_f32 v35, v24, v25
	v_and_b32_e32 v33, 16, v32
	v_cmp_eq_u32_e32 vcc, 0, v33
	v_cvt_pk_bf16_f32 v33, v28, v29
	v_and_or_b32 v64, v32, 15, s28
	v_lshrrev_b32_e32 v32, 2, v32
	v_mul_f32_e32 v30, v67, v30
	v_mul_f32_e32 v31, v67, v31
	v_mul_f32_e32 v26, v67, v26
	v_mul_f32_e32 v27, v67, v27
	v_cndmask_b32_e32 v24, v33, v35, vcc
	v_and_b32_e32 v32, 12, v32
	v_max_f32_e32 v30, 0, v30
	v_max_f32_e32 v31, 0, v31
	v_max_f32_e32 v26, 0, v26
	v_max_f32_e32 v27, 0, v27
	ds_bpermute_b32 v37, v132, v24
	v_mul_f32_e32 v20, v62, v20
	v_mul_f32_e32 v21, v62, v21
	v_mul_f32_e32 v22, v62, v22
	v_mul_f32_e32 v23, v62, v23
	v_mul_f32_e32 v16, v62, v16
	v_mul_f32_e32 v17, v62, v17
	v_mul_f32_e32 v18, v62, v18
	v_mul_f32_e32 v19, v62, v19
	v_add_u32_e32 v34, 12, v32
	v_pk_mul_f32 v[30:31], v[30:31], v[30:31]
	v_pk_mul_f32 v[26:27], v[26:27], v[26:27]
	v_max_f32_e32 v20, 0, v20
	v_max_f32_e32 v21, 0, v21
	v_max_f32_e32 v22, 0, v22
	v_max_f32_e32 v23, 0, v23
	v_max_f32_e32 v16, 0, v16
	v_max_f32_e32 v17, 0, v17
	v_max_f32_e32 v18, 0, v18
	v_max_f32_e32 v19, 0, v19
	v_cndmask_b32_e32 v32, v34, v32, vcc
	v_cvt_pk_bf16_f32 v34, v30, v31
	v_cvt_pk_bf16_f32 v26, v26, v27
	v_pk_mul_f32 v[20:21], v[20:21], v[20:21]
	v_pk_mul_f32 v[22:23], v[22:23], v[22:23]
	v_pk_mul_f32 v[16:17], v[16:17], v[16:17]
	v_pk_mul_f32 v[18:19], v[18:19], v[18:19]
	v_cndmask_b32_e32 v25, v34, v26, vcc
	v_cvt_pk_bf16_f32 v20, v20, v21
	v_cvt_pk_bf16_f32 v21, v22, v23
	v_cvt_pk_bf16_f32 v22, v16, v17
	v_cvt_pk_bf16_f32 v18, v18, v19
	ds_bpermute_b32 v36, v132, v25
	v_lshlrev_b64 v[24:25], 13, v[64:65]
	v_cndmask_b32_e32 v16, v20, v22, vcc
	v_cndmask_b32_e32 v17, v21, v18, vcc
	v_mul_f32_e32 v12, v48, v12
	v_mul_f32_e32 v13, v48, v13
	v_mul_f32_e32 v14, v48, v14
	v_mul_f32_e32 v15, v48, v15
	v_mul_f32_e32 v8, v48, v8
	v_mul_f32_e32 v9, v48, v9
	v_lshl_add_u64 v[28:29], s[50:51], 0, v[24:25]
	s_waitcnt lgkmcnt(1)
	v_cndmask_b32_e32 v24, v37, v33, vcc
	ds_bpermute_b32 v23, v132, v17
	ds_bpermute_b32 v33, v132, v16
	v_max_f32_e32 v12, 0, v12
	v_max_f32_e32 v13, 0, v13
	v_max_f32_e32 v14, 0, v14
	v_max_f32_e32 v15, 0, v15
	v_max_f32_e32 v8, 0, v8
	v_max_f32_e32 v9, 0, v9
	v_pk_mul_f32 v[12:13], v[12:13], v[12:13]
	v_pk_mul_f32 v[14:15], v[14:15], v[14:15]
	v_pk_mul_f32 v[8:9], v[8:9], v[8:9]
	v_cvt_pk_bf16_f32 v12, v12, v13
	v_cvt_pk_bf16_f32 v13, v14, v15
	v_cvt_pk_bf16_f32 v14, v8, v9
	v_lshl_add_u64 v[30:31], v[28:29], 0, s[6:7]
	v_lshlrev_b32_e32 v128, 1, v32
	v_mul_f32_e32 v10, v48, v10
	v_mul_f32_e32 v11, v48, v11
	v_cndmask_b32_e32 v8, v12, v14, vcc
	s_waitcnt lgkmcnt(2)
	v_cndmask_b32_e32 v27, v26, v36, vcc
	v_cndmask_b32_e32 v26, v35, v37, vcc
	v_cndmask_b32_e32 v25, v36, v34, vcc
	v_lshl_add_u64 v[16:17], v[30:31], 0, v[128:129]
	v_max_f32_e32 v10, 0, v10
	v_max_f32_e32 v11, 0, v11
	ds_bpermute_b32 v15, v132, v8
	v_mul_f32_e32 v4, v44, v4
	v_mul_f32_e32 v5, v44, v5
	v_mul_f32_e32 v6, v44, v6
	v_mul_f32_e32 v7, v44, v7
	v_mul_f32_e32 v0, v44, v0
	v_mul_f32_e32 v1, v44, v1
	v_mul_f32_e32 v2, v44, v2
	v_mul_f32_e32 v3, v44, v3
	global_store_dwordx4 v[16:17], v[24:27], off offset:256
	s_waitcnt lgkmcnt(2)
	v_cndmask_b32_e32 v17, v23, v21, vcc
	s_waitcnt lgkmcnt(1)
	v_cndmask_b32_e32 v16, v33, v20, vcc
	v_lshl_add_u64 v[20:21], v[28:29], 0, v[128:129]
	v_pk_mul_f32 v[10:11], v[10:11], v[10:11]
	v_max_f32_e32 v4, 0, v4
	v_max_f32_e32 v5, 0, v5
	v_max_f32_e32 v6, 0, v6
	v_max_f32_e32 v7, 0, v7
	v_max_f32_e32 v0, 0, v0
	v_max_f32_e32 v1, 0, v1
	v_max_f32_e32 v2, 0, v2
	v_max_f32_e32 v3, 0, v3
	v_lshl_add_u64 v[20:21], v[20:21], 0, s[30:31]
	v_cvt_pk_bf16_f32 v10, v10, v11
	v_pk_mul_f32 v[4:5], v[4:5], v[4:5]
	v_pk_mul_f32 v[6:7], v[6:7], v[6:7]
	v_pk_mul_f32 v[0:1], v[0:1], v[0:1]
	v_pk_mul_f32 v[2:3], v[2:3], v[2:3]
	v_cndmask_b32_e32 v9, v13, v10, vcc
	v_add_co_u32_e64 v8, s[0:1], s41, v20
	v_cvt_pk_bf16_f32 v4, v4, v5
	v_cvt_pk_bf16_f32 v5, v6, v7
	v_cvt_pk_bf16_f32 v6, v0, v1
	v_cvt_pk_bf16_f32 v2, v2, v3
	v_cndmask_b32_e32 v19, v18, v23, vcc
	v_cndmask_b32_e32 v18, v22, v33, vcc
	ds_bpermute_b32 v22, v132, v9
	v_addc_co_u32_e64 v9, s[0:1], 0, v21, s[0:1]
	v_cndmask_b32_e32 v0, v4, v6, vcc
	v_cndmask_b32_e32 v1, v5, v2, vcc
	global_store_dwordx4 v[8:9], v[16:19], off
	s_waitcnt lgkmcnt(1)
	v_cndmask_b32_e32 v8, v15, v12, vcc
	ds_bpermute_b32 v7, v132, v0
	ds_bpermute_b32 v12, v132, v1
	v_add_co_u32_e64 v0, s[0:1], s38, v20
	s_waitcnt lgkmcnt(2)
	v_cndmask_b32_e32 v11, v10, v22, vcc
	v_addc_co_u32_e64 v1, s[0:1], 0, v21, s[0:1]
	v_cndmask_b32_e32 v10, v14, v15, vcc
	v_cndmask_b32_e32 v9, v22, v13, vcc
	s_mul_i32 s0, s54, s45
	global_store_dwordx4 v[0:1], v[8:11], off
	s_waitcnt lgkmcnt(0)
	v_cndmask_b32_e32 v3, v2, v12, vcc
	v_cndmask_b32_e32 v2, v6, v7, vcc
	v_cndmask_b32_e32 v1, v12, v5, vcc
	v_cndmask_b32_e32 v0, v7, v4, vcc
	v_add_co_u32_e32 v4, vcc, 0x60000, v20
	s_add_i32 s2, s0, s83
	s_add_i32 s35, s35, s36
	s_add_i32 s37, s37, s45
	s_add_i32 s43, s43, s45
	v_addc_co_u32_e32 v5, vcc, 0, v21, vcc
	s_cmpk_lt_u32 s2, 0x100
	global_store_dwordx4 v[4:5], v[0:3], off
	s_cbranch_scc0 .LBB0_909
.LBB0_903:
	s_cmp_lg_u32 s32, 0
	s_cselect_b64 vcc, -1, 0
	v_mov_b32_e32 v15, v238
	s_add_i32 s0, s2, s34
	v_ashrrev_i32_e32 v0, 31, v15
	v_lshrrev_b32_e32 v0, 26, v0
	v_add_u32_e32 v0, v15, v0
	v_ashrrev_i32_e32 v14, 6, v0
	v_bfe_i32 v0, v15, 27, 1
	v_lshlrev_b32_e32 v20, 4, v15
	v_lshrrev_b32_e32 v0, 22, v0
	v_add_u32_e32 v0, v20, v0
	v_and_b32_e32 v0, 0xfffffc00, v0
	v_sub_u32_e32 v0, v20, v0
	v_lshrrev_b32_e32 v1, 4, v0
	v_bitop3_b32 v1, v1, v0, 32 bitop3:0x6c
	v_ashrrev_i32_e32 v0, 31, v0
	v_lshrrev_b32_e32 v0, 26, v0
	v_add_u32_e32 v0, v1, v0
	v_ashrrev_i32_e32 v16, 6, v0
	v_mul_i32_i24_e32 v3, 64, v16
	v_sub_u32_e32 v1, v1, v3
	v_ashrrev_i16_sdwa v1, v143, sext(v1) dst_sel:DWORD dst_unused:UNUSED_PAD src0_sel:DWORD src1_sel:BYTE_0
	v_bfe_i32 v18, v1, 0, 16
	v_add_u32_e32 v1, 0x2000, v20
	v_ashrrev_i32_e32 v3, 31, v1
	v_lshrrev_b32_e32 v3, 22, v3
	v_add_u32_e32 v3, v1, v3
	v_ashrrev_i32_e32 v17, 10, v3
	v_mul_i32_i24_e32 v3, 0x400, v17
	v_sub_u32_e32 v1, v1, v3
	v_lshrrev_b32_e32 v3, 4, v1
	v_bitop3_b32 v1, v3, v1, 32 bitop3:0x6c
	v_ashrrev_i32_e32 v4, 31, v1
	s_lshr_b32 s0, s0, 4
	v_lshrrev_b32_e32 v4, 26, v4
	s_and_b32 s0, s0, 0x78
	s_and_b32 s1, s2, 7
	v_add_u32_e32 v4, v1, v4
	s_or_b32 s6, s0, s1
	v_readfirstlane_b32 s3, v15
	v_lshlrev_b32_e32 v2, 3, v14
	v_lshlrev_b32_e32 v0, 5, v14
	v_ashrrev_i32_e32 v19, 6, v4
	v_and_b32_e32 v4, 0xc0, v4
	s_lshl_b32 s0, s2, 16
	v_and_b32_e32 v0, 32, v0
	v_sub_u32_e32 v1, v1, v4
	s_ashr_i32 s31, s3, 8
	v_and_b32_e32 v2, 0x1ffff0, v2
	s_and_b32 s0, s0, 0x780000
	v_add_u32_e32 v146, s44, v20
	v_add_u32_e32 v0, v0, v18
	v_lshlrev_b32_e32 v3, 3, v17
	v_lshlrev_b32_e32 v5, 5, v17
	v_ashrrev_i16_sdwa v1, v143, sext(v1) dst_sel:DWORD dst_unused:UNUSED_PAD src0_sel:DWORD src1_sel:BYTE_0
	v_add_lshl_u32 v2, v16, v2, 11
	s_add_u32 s28, s64, s0
	v_readfirstlane_b32 s1, v146
	v_add_u32_e32 v147, 0x2000, v146
	v_and_b32_e32 v5, 32, v5
	v_bfe_i32 v21, v1, 0, 16
	v_lshl_add_u32 v128, v0, 1, v2
	v_mov_b32_e32 v246, v128
	v_and_b32_e32 v0, 0x1ffff0, v3
	s_cbranch_vccnz .Lp7_skw0
	s_waitcnt vmcnt(0)
.Lp7_skw0:
	s_addc_u32 s29, s65, 0
	s_mov_b32 m0, s1
	v_readfirstlane_b32 s1, v147
	v_add_u32_e32 v1, v5, v21
	v_add_lshl_u32 v0, v19, v0, 11
	s_cbranch_vccnz .Lp7_skl0
	global_load_lds_dwordx4 v128, s[28:29]
.Lp7_skl0:
	s_mov_b32 m0, s1
	s_lshl_b32 s1, s6, 19
	v_add_u32_e32 v148, 0, v20
	v_lshl_add_u32 v0, v1, 1, v0
	v_mov_b32_e32 v247, v0
	s_add_u32 s56, s46, s1
	v_readfirstlane_b32 s30, v148
	v_add_u32_e32 v149, 0x2000, v148
	s_cbranch_vccnz .Lp7_skl1
	global_load_lds_dwordx4 v0, s[28:29]
.Lp7_skl1:
	s_addc_u32 s57, s47, 0
	s_mov_b32 m0, s30
	v_readfirstlane_b32 s30, v149
	s_bitset1_b32 s0, 18
	v_add_u32_e32 v151, s48, v20
	s_cbranch_vccnz .Lp7_skl2
	global_load_lds_dwordx4 v128, s[56:57]
.Lp7_skl2:
	s_mov_b32 m0, s30
	s_add_u32 s60, s64, s0
	v_readfirstlane_b32 s0, v151
	v_add_u32_e32 v152, 0x2000, v151
	s_cbranch_vccnz .Lp7_skl3
	global_load_lds_dwordx4 v0, s[56:57]
.Lp7_skl3:
	s_addc_u32 s61, s65, 0
	s_mov_b32 m0, s0
	v_readfirstlane_b32 s0, v152
	s_bitset1_b32 s1, 18
	v_add_u32_e32 v153, 0x4000, v148
	s_cbranch_vccnz .Lp7_skl4
	global_load_lds_dwordx4 v128, s[60:61]
.Lp7_skl4:
	s_mov_b32 m0, s0
	s_add_u32 s0, s46, s1
	v_readfirstlane_b32 s30, v153
	v_add_u32_e32 v154, 0x6000, v148
	s_cbranch_vccnz .Lp7_skl5
	global_load_lds_dwordx4 v0, s[60:61]
.Lp7_skl5:
	s_addc_u32 s1, s47, 0
	s_mov_b32 m0, s30
	v_readfirstlane_b32 s30, v154
	s_cbranch_vccnz .Lp7_skl6
	global_load_lds_dwordx4 v128, s[0:1]
.Lp7_skl6:
	s_mov_b32 m0, s30
	v_mov_b32_e32 v1, v129
	s_cbranch_vccnz .Lp7_skl7
	global_load_lds_dwordx4 v0, s[0:1]
.Lp7_skl7:
	v_lshl_add_u64 v[12:13], s[28:29], 0, v[128:129]
	v_lshl_add_u64 v[10:11], s[28:29], 0, v[0:1]
	v_lshl_add_u64 v[8:9], s[56:57], 0, v[128:129]
	v_lshl_add_u64 v[6:7], s[56:57], 0, v[0:1]
	v_lshl_add_u64 v[4:5], s[60:61], 0, v[128:129]
	s_cmp_lg_u32 s31, 1
	v_lshl_add_u64 v[2:3], s[60:61], 0, v[0:1]
	s_cbranch_scc1 .LBB0_905
	s_barrier
.LBB0_905:
	v_add_u32_e32 v155, s79, v20
	v_add_u32_e32 v156, 0x2000, v155
	v_readfirstlane_b32 s29, v155
	v_lshl_add_u64 v[130:131], s[0:1], 0, v[0:1]
	v_lshl_add_u64 v[0:1], v[12:13], 0, s[8:9]
	s_mov_b32 m0, s29
	v_readfirstlane_b32 s29, v156
	v_add_u32_e32 v158, 0x8000, v148
	s_cbranch_vccnz .Lp7_w4w
	s_waitcnt vmcnt(4)
	s_branch .Lp7_w4d
.Lp7_w4w:
	s_waitcnt vmcnt(20)
.Lp7_w4d:
	s_barrier
	global_load_lds_dwordx4 v[0:1], off
	v_lshl_add_u64 v[0:1], v[10:11], 0, s[8:9]
	s_mov_b32 m0, s29
	v_readfirstlane_b32 s29, v158
	v_add_u32_e32 v159, 0xa000, v148
	global_load_lds_dwordx4 v[0:1], off
	v_lshl_add_u64 v[0:1], v[8:9], 0, s[8:9]
	s_mov_b32 m0, s29
	v_readfirstlane_b32 s29, v159
	v_add_u32_e32 v160, s49, v20
	global_load_lds_dwordx4 v[0:1], off
	v_lshl_add_u64 v[0:1], v[6:7], 0, s[8:9]
	s_mov_b32 m0, s29
	v_readfirstlane_b32 s29, v160
	v_add_u32_e32 v161, 0x2000, v160
	global_load_lds_dwordx4 v[0:1], off
	v_lshl_add_u64 v[0:1], v[4:5], 0, s[8:9]
	s_mov_b32 m0, s29
	v_readfirstlane_b32 s29, v161
	global_load_lds_dwordx4 v[0:1], off
	v_lshl_add_u64 v[0:1], v[2:3], 0, s[8:9]
	s_mov_b32 m0, s29
	v_and_b32_e32 v22, 15, v15
	global_load_lds_dwordx4 v[0:1], off
	v_lshlrev_b32_e32 v1, 2, v15
	v_and_b32_e32 v23, 48, v15
	v_lshlrev_b32_e32 v0, 6, v22
	v_and_b32_e32 v1, 32, v1
	v_bitop3_b32 v0, v0, v1, v23 bitop3:0x36
	v_add_u32_e32 v2, s44, v0
	v_add_u32_e32 v3, s48, v0
	v_add_u32_e32 v4, s79, v0
	v_add_u32_e32 v5, s49, v0
	v_add_u32_e32 v6, 0, v0
	v_lshlrev_b32_e32 v0, 6, v15
	v_and_or_b32 v0, v0, s39, v23
	v_xad_u32 v162, v0, v1, 0
	v_lshlrev_b32_e32 v0, 14, v14
	v_and_b32_e32 v0, 0xffff8000, v0
	v_lshl_add_u32 v0, v16, 11, v0
	v_and_b32_e32 v1, 1, v14
	v_lshl_or_b32 v0, v1, 6, v0
	v_lshl_add_u64 v[132:133], s[0:1], 0, v[128:129]
	v_lshl_add_u32 v128, v18, 1, v0
	v_lshlrev_b32_e32 v0, 14, v17
	s_lshl_b32 s0, s35, 11
	v_and_b32_e32 v0, 0xffff8000, v0
	s_lshl_b32 s28, s6, 8
	s_and_b32 s6, s0, 0x780000
	s_and_b32 s0, s43, 7
	s_lshl_b32 s1, s37, 15
	v_lshl_add_u32 v0, v19, 11, v0
	v_and_b32_e32 v1, 1, v17
	s_and_b32 s1, s1, 0x3c00000
	s_lshl_b32 s0, s0, 19
	v_lshl_or_b32 v0, v1, 6, v0
	s_or_b32 s0, s1, s0
	s_mov_b32 s1, s7
	s_bfe_u32 s30, s3, 0x20006
	s_cbranch_vccnz .Lp7_w6w
	s_waitcnt vmcnt(6)
	s_branch .Lp7_w6d
.Lp7_w6w:
	s_waitcnt vmcnt(22)
.Lp7_w6d:
	s_lshl_b32 s57, s31, 13
	v_lshl_add_u32 v0, v21, 1, v0
	v_mov_b32_e32 v1, v129
	s_lshl_b32 s56, s30, 12
	s_or_b32 s60, s57, 0x800
	v_lshl_add_u64 v[136:137], s[6:7], 0, v[0:1]
	v_lshl_add_u64 v[140:141], s[0:1], 0, v[0:1]
	v_mov_b32_e32 v0, 0
	s_lshl_b32 s29, s31, 6
	s_or_b32 s31, s57, 0x1000
	s_or_b32 s55, s57, 0x1800
	v_lshl_add_u64 v[134:135], s[6:7], 0, v[128:129]
	v_lshl_add_u64 v[138:139], s[0:1], 0, v[128:129]
	s_mov_b32 s6, -2
	v_add_u32_e32 v163, s56, v2
	v_add_u32_e32 v144, s57, v6
	v_add_u32_e32 v128, s60, v162
	v_add_u32_e32 v157, s56, v3
	v_add_u32_e32 v150, s56, v4
	v_add_u32_e32 v145, s56, v5
	s_mov_b64 s[0:1], s[52:53]
	v_mov_b32_e32 v1, v0
	v_mov_b32_e32 v2, v0
	v_mov_b32_e32 v3, v0
	v_mov_b32_e32 v4, v0
	v_mov_b32_e32 v5, v0
	v_mov_b32_e32 v6, v0
	v_mov_b32_e32 v7, v0
	v_mov_b32_e32 v8, v0
	v_mov_b32_e32 v9, v0
	v_mov_b32_e32 v10, v0
	v_mov_b32_e32 v11, v0
	v_mov_b32_e32 v12, v0
	v_mov_b32_e32 v13, v0
	v_mov_b32_e32 v14, v0
	v_mov_b32_e32 v15, v0
	v_mov_b32_e32 v16, v0
	v_mov_b32_e32 v17, v0
	v_mov_b32_e32 v18, v0
	v_mov_b32_e32 v19, v0
	v_mov_b32_e32 v20, v0
	v_mov_b32_e32 v21, v0
	v_mov_b32_e32 v22, v0
	v_mov_b32_e32 v23, v0
	v_mov_b32_e32 v24, v0
	v_mov_b32_e32 v25, v0
	v_mov_b32_e32 v26, v0
	v_mov_b32_e32 v27, v0
	v_mov_b32_e32 v28, v0
	v_mov_b32_e32 v29, v0
	v_mov_b32_e32 v30, v0
	v_mov_b32_e32 v31, v0
	v_mov_b32_e32 v32, v0
	v_mov_b32_e32 v33, v0
	v_mov_b32_e32 v34, v0
	v_mov_b32_e32 v35, v0
	v_mov_b32_e32 v36, v0
	v_mov_b32_e32 v37, v0
	v_mov_b32_e32 v38, v0
	v_mov_b32_e32 v39, v0
	v_mov_b32_e32 v40, v0
	v_mov_b32_e32 v41, v0
	v_mov_b32_e32 v42, v0
	v_mov_b32_e32 v43, v0
	v_mov_b32_e32 v44, v0
	v_mov_b32_e32 v45, v0
	v_mov_b32_e32 v46, v0
	v_mov_b32_e32 v47, v0
	v_mov_b32_e32 v48, v0
	v_mov_b32_e32 v49, v0
	v_mov_b32_e32 v50, v0
	v_mov_b32_e32 v51, v0
	v_mov_b32_e32 v52, v0
	v_mov_b32_e32 v53, v0
	v_mov_b32_e32 v54, v0
	v_mov_b32_e32 v55, v0
	v_mov_b32_e32 v56, v0
	v_mov_b32_e32 v57, v0
	v_mov_b32_e32 v58, v0
	v_mov_b32_e32 v59, v0
	v_mov_b32_e32 v60, v0
	v_mov_b32_e32 v61, v0
	v_mov_b32_e32 v62, v0
	v_mov_b32_e32 v63, v0
	v_mov_b32_e32 v64, v0
	v_mov_b32_e32 v65, v0
	v_mov_b32_e32 v66, v0
	v_mov_b32_e32 v67, v0
	v_mov_b32_e32 v68, v0
	v_mov_b32_e32 v69, v0
	v_mov_b32_e32 v70, v0
	v_mov_b32_e32 v71, v0
	v_mov_b32_e32 v72, v0
	v_mov_b32_e32 v73, v0
	v_mov_b32_e32 v74, v0
	v_mov_b32_e32 v75, v0
	v_mov_b32_e32 v76, v0
	v_mov_b32_e32 v77, v0
	v_mov_b32_e32 v78, v0
	v_mov_b32_e32 v79, v0
	v_mov_b32_e32 v80, v0
	v_mov_b32_e32 v81, v0
	v_mov_b32_e32 v82, v0
	v_mov_b32_e32 v83, v0
	v_mov_b32_e32 v84, v0
	v_mov_b32_e32 v85, v0
	v_mov_b32_e32 v86, v0
	v_mov_b32_e32 v87, v0
	v_mov_b32_e32 v88, v0
	v_mov_b32_e32 v89, v0
	v_mov_b32_e32 v90, v0
	v_mov_b32_e32 v91, v0
	v_mov_b32_e32 v92, v0
	v_mov_b32_e32 v93, v0
	v_mov_b32_e32 v94, v0
	v_mov_b32_e32 v95, v0
	v_mov_b32_e32 v96, v0
	v_mov_b32_e32 v97, v0
	v_mov_b32_e32 v98, v0
	v_mov_b32_e32 v99, v0
	v_mov_b32_e32 v100, v0
	v_mov_b32_e32 v101, v0
	v_mov_b32_e32 v102, v0
	v_mov_b32_e32 v103, v0
	v_mov_b32_e32 v104, v0
	v_mov_b32_e32 v105, v0
	v_mov_b32_e32 v106, v0
	v_mov_b32_e32 v107, v0
	v_mov_b32_e32 v108, v0
	v_mov_b32_e32 v109, v0
	v_mov_b32_e32 v110, v0
	v_mov_b32_e32 v111, v0
	v_mov_b32_e32 v112, v0
	v_mov_b32_e32 v113, v0
	v_mov_b32_e32 v114, v0
	v_mov_b32_e32 v115, v0
	v_mov_b32_e32 v116, v0
	v_mov_b32_e32 v117, v0
	v_mov_b32_e32 v118, v0
	v_mov_b32_e32 v119, v0
	v_mov_b32_e32 v120, v0
	v_mov_b32_e32 v121, v0
	v_mov_b32_e32 v122, v0
	v_mov_b32_e32 v123, v0
	v_mov_b32_e32 v124, v0
	v_mov_b32_e32 v125, v0
	v_mov_b32_e32 v126, v0
	v_mov_b32_e32 v127, v0
	s_barrier

	.amdhsa_kernel _Z4mega4Args
		.amdhsa_group_segment_fixed_size 0
		.amdhsa_private_segment_fixed_size 0
		.amdhsa_kernarg_size 408
		.amdhsa_user_sgpr_count 2
		.amdhsa_user_sgpr_dispatch_ptr 0
		.amdhsa_user_sgpr_queue_ptr 0
		.amdhsa_user_sgpr_kernarg_segment_ptr 1
		.amdhsa_user_sgpr_dispatch_id 0
		.amdhsa_user_sgpr_kernarg_preload_length 0
		.amdhsa_user_sgpr_kernarg_preload_offset 0
		.amdhsa_user_sgpr_private_segment_size 0
		.amdhsa_uses_dynamic_stack 0
		.amdhsa_enable_private_segment 0
		.amdhsa_system_sgpr_workgroup_id_x 1
		.amdhsa_system_sgpr_workgroup_id_y 0
		.amdhsa_system_sgpr_workgroup_id_z 0
		.amdhsa_system_sgpr_workgroup_info 0
		.amdhsa_system_vgpr_workitem_id 2
		.amdhsa_next_free_vgpr 256
		.amdhsa_next_free_sgpr 102
		.amdhsa_accum_offset 256
		.amdhsa_reserve_vcc 1
		.amdhsa_float_round_mode_32 0
		.amdhsa_float_round_mode_16_64 0
		.amdhsa_float_denorm_mode_32 3
		.amdhsa_float_denorm_mode_16_64 3
		.amdhsa_dx10_clamp 1
		.amdhsa_ieee_mode 1
		.amdhsa_fp16_overflow 0
		.amdhsa_tg_split 0
		.amdhsa_exception_fp_ieee_invalid_op 0
		.amdhsa_exception_fp_denorm_src 0
		.amdhsa_exception_fp_ieee_div_zero 0
		.amdhsa_exception_fp_ieee_overflow 0
		.amdhsa_exception_fp_ieee_underflow 0
		.amdhsa_exception_fp_ieee_inexact 0
		.amdhsa_exception_int_div_zero 0
	.end_amdhsa_kernel

amdhsa.kernels:
  - .agpr_count:     0
    .args:
      - .offset:         0
        .size:           152
        .value_kind:     by_value
      - .offset:         152
        .size:           4
        .value_kind:     hidden_block_count_x
      - .offset:         156
        .size:           4
        .value_kind:     hidden_block_count_y
      - .offset:         160
        .size:           4
        .value_kind:     hidden_block_count_z
      - .offset:         164
        .size:           2
        .value_kind:     hidden_group_size_x
      - .offset:         166
        .size:           2
        .value_kind:     hidden_group_size_y
      - .offset:         168
        .size:           2
        .value_kind:     hidden_group_size_z
      - .offset:         170
        .size:           2
        .value_kind:     hidden_remainder_x
      - .offset:         172
        .size:           2
        .value_kind:     hidden_remainder_y
      - .offset:         174
        .size:           2
        .value_kind:     hidden_remainder_z
      - .offset:         192
        .size:           8
        .value_kind:     hidden_global_offset_x
      - .offset:         200
        .size:           8
        .value_kind:     hidden_global_offset_y
      - .offset:         208
        .size:           8
        .value_kind:     hidden_global_offset_z
      - .offset:         216
        .size:           2
        .value_kind:     hidden_grid_dims
      - .offset:         240
        .size:           8
        .value_kind:     hidden_multigrid_sync_arg
      - .offset:         272
        .size:           4
        .value_kind:     hidden_dynamic_lds_size
    .group_segment_fixed_size: 0
    .kernarg_segment_align: 8
    .kernarg_segment_size: 408
    .language:       OpenCL C
    .language_version:
      - 2
      - 0
    .max_flat_workgroup_size: 512
    .name:           _Z4mega4Args
    .private_segment_fixed_size: 0
    .sgpr_count:     108
    .sgpr_spill_count: 41
    .symbol:         _Z4mega4Args.kd
    .uniform_work_group_size: 1
    .uses_dynamic_stack: false
    .vgpr_count:     256
    .vgpr_spill_count: 0
    .wavefront_size: 64
